# phase-0 weight-prep tile loader unrolled: 16 loads in flight per 64x64 tile instead of 8 serial round trips (w_in, w_out, w_gate, w_up)
# speedup vs baseline: 1.0317x; 1.0074x over previous
; DI int opaque_tid() { int t = threadIdx.x; asm volatile("" : "+v"(t)); return t; }
; DI void wt_tile(const float* __restrict__ W, int K, int N, const float* __restrict__ g, u16* __restrict__ Wt, int k0, int n0, int mapmode, float* tile) {
;   const int tid = opaque_tid();
;   for (int i = tid; i < 4096; i += NTHR) {
;     int kk = i >> 6, nn = i & 63, n = n0 + nn;
;     float v = 0.f;
;     if (n < N) { v = W[(size_t)(k0 + kk) * N + n]; if (g) v *= g[k0 + kk]; }
;     tile[kk * 65 + nn] = v;
;   }
.Lprep_fast_2:
	s_andn2_b64 vcc, exec, s[58:59]
	s_cbranch_vccnz .LBB0_342
	v_ashrrev_i32_e32 v8, 6, v7
	v_add_u32_e32 v4, s11, v8
	s_movk_i32 s16, 0x2c00
	v_mad_i64_i32 v[10:11], s[16:17], v4, s16, v[2:3]
	v_ashrrev_i32_e32 v5, 31, v4
	v_lshl_add_u64 v[4:5], v[4:5], 2, s[6:7]
	global_load_dword v20, v[10:11], off
	global_load_dword v28, v[4:5], off
	v_add_co_u32_e32 v10, vcc, 0x16000, v10
	s_nop 1
	v_addc_co_u32_e32 v11, vcc, 0, v11, vcc
	global_load_dword v21, v[10:11], off
	global_load_dword v29, v[4:5], off offset:32
	v_add_co_u32_e32 v10, vcc, 0x16000, v10
	s_nop 1
	v_addc_co_u32_e32 v11, vcc, 0, v11, vcc
	global_load_dword v22, v[10:11], off
	global_load_dword v30, v[4:5], off offset:64
	v_add_co_u32_e32 v10, vcc, 0x16000, v10
	s_nop 1
	v_addc_co_u32_e32 v11, vcc, 0, v11, vcc
	global_load_dword v23, v[10:11], off
	global_load_dword v31, v[4:5], off offset:96
	v_add_co_u32_e32 v10, vcc, 0x16000, v10
	s_nop 1
	v_addc_co_u32_e32 v11, vcc, 0, v11, vcc
	global_load_dword v24, v[10:11], off
	global_load_dword v32, v[4:5], off offset:128
	v_add_co_u32_e32 v10, vcc, 0x16000, v10
	s_nop 1
	v_addc_co_u32_e32 v11, vcc, 0, v11, vcc
	global_load_dword v25, v[10:11], off
	global_load_dword v33, v[4:5], off offset:160
	v_add_co_u32_e32 v10, vcc, 0x16000, v10
	s_nop 1
	v_addc_co_u32_e32 v11, vcc, 0, v11, vcc
	global_load_dword v26, v[10:11], off
	global_load_dword v34, v[4:5], off offset:192
	v_add_co_u32_e32 v10, vcc, 0x16000, v10
	s_nop 1
	v_addc_co_u32_e32 v11, vcc, 0, v11, vcc
	global_load_dword v27, v[10:11], off
	global_load_dword v35, v[4:5], off offset:224
	v_mad_u64_u32 v[36:37], s[16:17], v8, s84, v[0:1]
	s_waitcnt vmcnt(14)
	v_mul_f32_e32 v20, v20, v28
	ds_write_b32 v36, v20
	s_waitcnt vmcnt(12)
	v_mul_f32_e32 v21, v21, v29
	ds_write_b32 v36, v21 offset:2080
	s_waitcnt vmcnt(10)
	v_mul_f32_e32 v22, v22, v30
	ds_write_b32 v36, v22 offset:4160
	s_waitcnt vmcnt(8)
	v_mul_f32_e32 v23, v23, v31
	ds_write_b32 v36, v23 offset:6240
	s_waitcnt vmcnt(6)
	v_mul_f32_e32 v24, v24, v32
	ds_write_b32 v36, v24 offset:8320
	s_waitcnt vmcnt(4)
	v_mul_f32_e32 v25, v25, v33
	ds_write_b32 v36, v25 offset:10400
	s_waitcnt vmcnt(2)
	v_mul_f32_e32 v26, v26, v34
	ds_write_b32 v36, v26 offset:12480
	s_waitcnt vmcnt(0)
	v_mul_f32_e32 v27, v27, v35
	ds_write_b32 v36, v27 offset:14560
	s_branch .LBB0_405

; DI int opaque_tid() { int t = threadIdx.x; asm volatile("" : "+v"(t)); return t; }
; DI void wt_tile(const float* __restrict__ W, int K, int N, const float* __restrict__ g, u16* __restrict__ Wt, int k0, int n0, int mapmode, float* tile) {
;   const int tid = opaque_tid();
;   for (int i = tid; i < 4096; i += NTHR) {
;     int kk = i >> 6, nn = i & 63, n = n0 + nn;
;     float v = 0.f;
;     if (n < N) { v = W[(size_t)(k0 + kk) * N + n]; if (g) v *= g[k0 + kk]; }
;     tile[kk * 65 + nn] = v;
;   }
.Lprep_fast_4:
	s_andn2_b64 vcc, exec, s[60:61]
	s_cbranch_vccnz .LBB0_360
	v_ashrrev_i32_e32 v8, 6, v7
	v_add_u32_e32 v4, s11, v8
	v_ashrrev_i32_e32 v5, 31, v4
	v_lshlrev_b64 v[10:11], 12, v[4:5]
	v_lshl_add_u64 v[10:11], v[2:3], 0, v[10:11]
	v_ashrrev_i32_e32 v5, 31, v4
	v_lshl_add_u64 v[4:5], v[4:5], 2, s[6:7]
	global_load_dword v20, v[10:11], off
	global_load_dword v28, v[4:5], off
	v_add_co_u32_e32 v10, vcc, 0x8000, v10
	s_nop 1
	v_addc_co_u32_e32 v11, vcc, 0, v11, vcc
	global_load_dword v21, v[10:11], off
	global_load_dword v29, v[4:5], off offset:32
	v_add_co_u32_e32 v10, vcc, 0x8000, v10
	s_nop 1
	v_addc_co_u32_e32 v11, vcc, 0, v11, vcc
	global_load_dword v22, v[10:11], off
	global_load_dword v30, v[4:5], off offset:64
	v_add_co_u32_e32 v10, vcc, 0x8000, v10
	s_nop 1
	v_addc_co_u32_e32 v11, vcc, 0, v11, vcc
	global_load_dword v23, v[10:11], off
	global_load_dword v31, v[4:5], off offset:96
	v_add_co_u32_e32 v10, vcc, 0x8000, v10
	s_nop 1
	v_addc_co_u32_e32 v11, vcc, 0, v11, vcc
	global_load_dword v24, v[10:11], off
	global_load_dword v32, v[4:5], off offset:128
	v_add_co_u32_e32 v10, vcc, 0x8000, v10
	s_nop 1
	v_addc_co_u32_e32 v11, vcc, 0, v11, vcc
	global_load_dword v25, v[10:11], off
	global_load_dword v33, v[4:5], off offset:160
	v_add_co_u32_e32 v10, vcc, 0x8000, v10
	s_nop 1
	v_addc_co_u32_e32 v11, vcc, 0, v11, vcc
	global_load_dword v26, v[10:11], off
	global_load_dword v34, v[4:5], off offset:192
	v_add_co_u32_e32 v10, vcc, 0x8000, v10
	s_nop 1
	v_addc_co_u32_e32 v11, vcc, 0, v11, vcc
	global_load_dword v27, v[10:11], off
	global_load_dword v35, v[4:5], off offset:224
	v_mad_u64_u32 v[36:37], s[16:17], v8, s84, v[0:1]
	s_waitcnt vmcnt(14)
	v_mul_f32_e32 v20, v20, v28
	ds_write_b32 v36, v20
	s_waitcnt vmcnt(12)
	v_mul_f32_e32 v21, v21, v29
	ds_write_b32 v36, v21 offset:2080
	s_waitcnt vmcnt(10)
	v_mul_f32_e32 v22, v22, v30
	ds_write_b32 v36, v22 offset:4160
	s_waitcnt vmcnt(8)
	v_mul_f32_e32 v23, v23, v31
	ds_write_b32 v36, v23 offset:6240
	s_waitcnt vmcnt(6)
	v_mul_f32_e32 v24, v24, v32
	ds_write_b32 v36, v24 offset:8320
	s_waitcnt vmcnt(4)
	v_mul_f32_e32 v25, v25, v33
	ds_write_b32 v36, v25 offset:10400
	s_waitcnt vmcnt(2)
	v_mul_f32_e32 v26, v26, v34
	ds_write_b32 v36, v26 offset:12480
	s_waitcnt vmcnt(0)
	v_mul_f32_e32 v27, v27, v35
	ds_write_b32 v36, v27 offset:14560
	s_branch .LBB0_362

; DI int opaque_tid() { int t = threadIdx.x; asm volatile("" : "+v"(t)); return t; }
; DI void wt_tile(const float* __restrict__ W, int K, int N, const float* __restrict__ g, u16* __restrict__ Wt, int k0, int n0, int mapmode, float* tile) {
;   const int tid = opaque_tid();
;   for (int i = tid; i < 4096; i += NTHR) {
;     int kk = i >> 6, nn = i & 63, n = n0 + nn;
;     float v = 0.f;
;     if (n < N) { v = W[(size_t)(k0 + kk) * N + n]; if (g) v *= g[k0 + kk]; }
;     tile[kk * 65 + nn] = v;
;   }
.Lprep_fast_7:
	s_andn2_b64 vcc, exec, s[66:67]
	s_cbranch_vccnz .LBB0_394
	s_andn2_b64 vcc, exec, s[4:5]
	s_cbranch_vccnz .LBB0_394
	v_ashrrev_i32_e32 v8, 6, v7
	v_add_u32_e32 v4, s16, v8
	s_movk_i32 s17, 0x2680
	v_mad_i64_i32 v[10:11], s[18:19], v4, s17, v[2:3]
	v_ashrrev_i32_e32 v5, 31, v4
	v_lshl_add_u64 v[4:5], v[4:5], 2, s[6:7]
	global_load_dword v20, v[10:11], off
	global_load_dword v28, v[4:5], off
	v_add_co_u32_e32 v10, vcc, 0x13400, v10
	s_nop 1
	v_addc_co_u32_e32 v11, vcc, 0, v11, vcc
	global_load_dword v21, v[10:11], off
	global_load_dword v29, v[4:5], off offset:32
	v_add_co_u32_e32 v10, vcc, 0x13400, v10
	s_nop 1
	v_addc_co_u32_e32 v11, vcc, 0, v11, vcc
	global_load_dword v22, v[10:11], off
	global_load_dword v30, v[4:5], off offset:64
	v_add_co_u32_e32 v10, vcc, 0x13400, v10
	s_nop 1
	v_addc_co_u32_e32 v11, vcc, 0, v11, vcc
	global_load_dword v23, v[10:11], off
	global_load_dword v31, v[4:5], off offset:96
	v_add_co_u32_e32 v10, vcc, 0x13400, v10
	s_nop 1
	v_addc_co_u32_e32 v11, vcc, 0, v11, vcc
	global_load_dword v24, v[10:11], off
	global_load_dword v32, v[4:5], off offset:128
	v_add_co_u32_e32 v10, vcc, 0x13400, v10
	s_nop 1
	v_addc_co_u32_e32 v11, vcc, 0, v11, vcc
	global_load_dword v25, v[10:11], off
	global_load_dword v33, v[4:5], off offset:160
	v_add_co_u32_e32 v10, vcc, 0x13400, v10
	s_nop 1
	v_addc_co_u32_e32 v11, vcc, 0, v11, vcc
	global_load_dword v26, v[10:11], off
	global_load_dword v34, v[4:5], off offset:192
	v_add_co_u32_e32 v10, vcc, 0x13400, v10
	s_nop 1
	v_addc_co_u32_e32 v11, vcc, 0, v11, vcc
	global_load_dword v27, v[10:11], off
	global_load_dword v35, v[4:5], off offset:224
	v_mad_u64_u32 v[36:37], s[10:11], v8, s84, v[0:1]
	s_waitcnt vmcnt(14)
	v_mul_f32_e32 v20, v20, v28
	ds_write_b32 v36, v20
	s_waitcnt vmcnt(12)
	v_mul_f32_e32 v21, v21, v29
	ds_write_b32 v36, v21 offset:2080
	s_waitcnt vmcnt(10)
	v_mul_f32_e32 v22, v22, v30
	ds_write_b32 v36, v22 offset:4160
	s_waitcnt vmcnt(8)
	v_mul_f32_e32 v23, v23, v31
	ds_write_b32 v36, v23 offset:6240
	s_waitcnt vmcnt(6)
	v_mul_f32_e32 v24, v24, v32
	ds_write_b32 v36, v24 offset:8320
	s_waitcnt vmcnt(4)
	v_mul_f32_e32 v25, v25, v33
	ds_write_b32 v36, v25 offset:10400
	s_waitcnt vmcnt(2)
	v_mul_f32_e32 v26, v26, v34
	ds_write_b32 v36, v26 offset:12480
	s_waitcnt vmcnt(0)
	v_mul_f32_e32 v27, v27, v35
	ds_write_b32 v36, v27 offset:14560
	s_branch .LBB0_397
